# decode-row NSA PV loop: FLAT V-row loads replaced by global loads so eight stay in flight per batch
# speedup vs baseline: 1.0119x; 1.0041x over previous
; DI void snsa_unit(const Args& a, LAS unsigned char* lds, int s, int g) {
;     ...
; #pragma unroll 1
;           for (int k0 = ksl; k0 < nkeys; k0 += 256) {
;               f32x4 v[8];
; #pragma unroll
;               for (int u = 0; u < 8; ++u) { const int kk = k0 + 32 * u; const int kc = kk < nkeys ? kk : k0;
;                   if (br == 0) { const u32x2 w = *(const u32x2*)(vcb + (size_t)kc * 64 + 4 * c16); v[u] = (f32x4){bf2f(w.x & 0xffffu), bf2f(w.x >> 16), bf2f(w.y & 0xffffu), bf2f(w.y >> 16)}; }
;                   else v[u] = *(const f32x4*)((const float*)(uintptr_t)VP[kc] + 4 * c16); }
.LBB0_1652:
	s_mov_b64 s[18:19], -1
	s_and_b64 vcc, exec, s[8:9]
	v_lshlrev_b32_e32 v70, 2, v76
	s_cbranch_vccz .LBB0_1654
	ds_read_b64 v[18:19], v89
	s_mov_b64 s[18:19], 0
	s_waitcnt lgkmcnt(0)
	v_lshl_add_u64 v[18:19], v[18:19], 0, v[70:71]
	global_load_dwordx4 v[62:65], v[18:19], off

; DI void snsa_unit(const Args& a, LAS unsigned char* lds, int s, int g) {
;     ...
; #pragma unroll 1
;           for (int k0 = ksl; k0 < nkeys; k0 += 256) {
;               f32x4 v[8];
; #pragma unroll
;               for (int u = 0; u < 8; ++u) { const int kk = k0 + 32 * u; const int kc = kk < nkeys ? kk : k0;
;                   if (br == 0) { const u32x2 w = *(const u32x2*)(vcb + (size_t)kc * 64 + 4 * c16); v[u] = (f32x4){bf2f(w.x & 0xffffu), bf2f(w.x >> 16), bf2f(w.y & 0xffffu), bf2f(w.y >> 16)}; }
;                   else v[u] = *(const f32x4*)((const float*)(uintptr_t)VP[kc] + 4 * c16); }
.LBB0_1656:
	v_add_u32_e32 v18, 32, v90
	v_cmp_gt_i32_e64 s[36:37], s2, v18
	v_cndmask_b32_e64 v19, 0, 1, s[8:9]
	v_cmp_ne_u32_e64 s[38:39], 1, v19
	v_cndmask_b32_e64 v18, v90, v18, s[36:37]
	s_andn2_b64 vcc, exec, s[8:9]
	s_mov_b64 s[18:19], -1
	s_cbranch_vccnz .LBB0_1658
	v_lshl_add_u32 v19, v18, 3, 0
	ds_read_b64 v[20:21], v19 offset:16384
	s_mov_b64 s[18:19], 0
	s_waitcnt lgkmcnt(0)
	v_lshl_add_u64 v[20:21], v[20:21], 0, v[70:71]
	global_load_dwordx4 v[58:61], v[20:21], off

; DI void snsa_unit(const Args& a, LAS unsigned char* lds, int s, int g) {
;     ...
; #pragma unroll 1
;           for (int k0 = ksl; k0 < nkeys; k0 += 256) {
;               f32x4 v[8];
; #pragma unroll
;               for (int u = 0; u < 8; ++u) { const int kk = k0 + 32 * u; const int kc = kk < nkeys ? kk : k0;
;                   if (br == 0) { const u32x2 w = *(const u32x2*)(vcb + (size_t)kc * 64 + 4 * c16); v[u] = (f32x4){bf2f(w.x & 0xffffu), bf2f(w.x >> 16), bf2f(w.y & 0xffffu), bf2f(w.y >> 16)}; }
;                   else v[u] = *(const f32x4*)((const float*)(uintptr_t)VP[kc] + 4 * c16); }
.LBB0_1660:
	v_add_u32_e32 v18, 64, v90
	v_cmp_gt_i32_e64 s[34:35], s2, v18
	s_and_b64 vcc, exec, s[38:39]
	s_mov_b64 s[18:19], -1
	v_cndmask_b32_e64 v18, v90, v18, s[34:35]
	s_cbranch_vccnz .LBB0_1662
	v_lshl_add_u32 v19, v18, 3, 0
	ds_read_b64 v[20:21], v19 offset:16384
	s_mov_b64 s[18:19], 0
	s_waitcnt lgkmcnt(0)
	v_lshl_add_u64 v[20:21], v[20:21], 0, v[70:71]
	global_load_dwordx4 v[54:57], v[20:21], off

; DI void snsa_unit(const Args& a, LAS unsigned char* lds, int s, int g) {
;     ...
; #pragma unroll 1
;           for (int k0 = ksl; k0 < nkeys; k0 += 256) {
;               f32x4 v[8];
; #pragma unroll
;               for (int u = 0; u < 8; ++u) { const int kk = k0 + 32 * u; const int kc = kk < nkeys ? kk : k0;
;                   if (br == 0) { const u32x2 w = *(const u32x2*)(vcb + (size_t)kc * 64 + 4 * c16); v[u] = (f32x4){bf2f(w.x & 0xffffu), bf2f(w.x >> 16), bf2f(w.y & 0xffffu), bf2f(w.y >> 16)}; }
;                   else v[u] = *(const f32x4*)((const float*)(uintptr_t)VP[kc] + 4 * c16); }
.LBB0_1664:
	v_add_u32_e32 v18, 0x60, v90
	v_cmp_gt_i32_e64 s[30:31], s2, v18
	s_and_b64 vcc, exec, s[38:39]
	s_mov_b64 s[18:19], -1
	v_cndmask_b32_e64 v18, v90, v18, s[30:31]
	s_cbranch_vccnz .LBB0_1666
	v_lshl_add_u32 v19, v18, 3, 0
	ds_read_b64 v[20:21], v19 offset:16384
	s_mov_b64 s[18:19], 0
	s_waitcnt lgkmcnt(0)
	v_lshl_add_u64 v[20:21], v[20:21], 0, v[70:71]
	global_load_dwordx4 v[50:53], v[20:21], off

; DI void snsa_unit(const Args& a, LAS unsigned char* lds, int s, int g) {
;     ...
; #pragma unroll 1
;           for (int k0 = ksl; k0 < nkeys; k0 += 256) {
;               f32x4 v[8];
; #pragma unroll
;               for (int u = 0; u < 8; ++u) { const int kk = k0 + 32 * u; const int kc = kk < nkeys ? kk : k0;
;                   if (br == 0) { const u32x2 w = *(const u32x2*)(vcb + (size_t)kc * 64 + 4 * c16); v[u] = (f32x4){bf2f(w.x & 0xffffu), bf2f(w.x >> 16), bf2f(w.y & 0xffffu), bf2f(w.y >> 16)}; }
;                   else v[u] = *(const f32x4*)((const float*)(uintptr_t)VP[kc] + 4 * c16); }
.LBB0_1668:
	v_add_u32_e32 v18, 0x80, v90
	v_cmp_gt_i32_e64 s[28:29], s2, v18
	s_and_b64 vcc, exec, s[38:39]
	s_mov_b64 s[18:19], -1
	v_cndmask_b32_e64 v18, v90, v18, s[28:29]
	s_cbranch_vccnz .LBB0_1670
	v_lshl_add_u32 v19, v18, 3, 0
	ds_read_b64 v[20:21], v19 offset:16384
	s_mov_b64 s[18:19], 0
	s_waitcnt lgkmcnt(0)
	v_lshl_add_u64 v[20:21], v[20:21], 0, v[70:71]
	global_load_dwordx4 v[46:49], v[20:21], off

; DI void snsa_unit(const Args& a, LAS unsigned char* lds, int s, int g) {
;     ...
; #pragma unroll 1
;           for (int k0 = ksl; k0 < nkeys; k0 += 256) {
;               f32x4 v[8];
; #pragma unroll
;               for (int u = 0; u < 8; ++u) { const int kk = k0 + 32 * u; const int kc = kk < nkeys ? kk : k0;
;                   if (br == 0) { const u32x2 w = *(const u32x2*)(vcb + (size_t)kc * 64 + 4 * c16); v[u] = (f32x4){bf2f(w.x & 0xffffu), bf2f(w.x >> 16), bf2f(w.y & 0xffffu), bf2f(w.y >> 16)}; }
;                   else v[u] = *(const f32x4*)((const float*)(uintptr_t)VP[kc] + 4 * c16); }
.LBB0_1672:
	v_add_u32_e32 v18, 0xa0, v90
	v_cmp_gt_i32_e64 s[26:27], s2, v18
	s_and_b64 vcc, exec, s[38:39]
	s_mov_b64 s[18:19], -1
	v_cndmask_b32_e64 v18, v90, v18, s[26:27]
	s_cbranch_vccnz .LBB0_1674
	v_lshl_add_u32 v19, v18, 3, 0
	ds_read_b64 v[20:21], v19 offset:16384
	s_mov_b64 s[18:19], 0
	s_waitcnt lgkmcnt(0)
	v_lshl_add_u64 v[20:21], v[20:21], 0, v[70:71]
	global_load_dwordx4 v[42:45], v[20:21], off

; DI void snsa_unit(const Args& a, LAS unsigned char* lds, int s, int g) {
;     ...
; #pragma unroll 1
;           for (int k0 = ksl; k0 < nkeys; k0 += 256) {
;               f32x4 v[8];
; #pragma unroll
;               for (int u = 0; u < 8; ++u) { const int kk = k0 + 32 * u; const int kc = kk < nkeys ? kk : k0;
;                   if (br == 0) { const u32x2 w = *(const u32x2*)(vcb + (size_t)kc * 64 + 4 * c16); v[u] = (f32x4){bf2f(w.x & 0xffffu), bf2f(w.x >> 16), bf2f(w.y & 0xffffu), bf2f(w.y >> 16)}; }
;                   else v[u] = *(const f32x4*)((const float*)(uintptr_t)VP[kc] + 4 * c16); }
.LBB0_1676:
	v_add_u32_e32 v18, 0xc0, v90
	v_cmp_gt_i32_e64 s[24:25], s2, v18
	s_and_b64 vcc, exec, s[38:39]
	s_mov_b64 s[18:19], -1
	v_cndmask_b32_e64 v18, v90, v18, s[24:25]
	s_cbranch_vccnz .LBB0_1678
	v_lshl_add_u32 v19, v18, 3, 0
	ds_read_b64 v[20:21], v19 offset:16384
	s_mov_b64 s[18:19], 0
	s_waitcnt lgkmcnt(0)
	v_lshl_add_u64 v[20:21], v[20:21], 0, v[70:71]
	global_load_dwordx4 v[38:41], v[20:21], off

; DI void snsa_unit(const Args& a, LAS unsigned char* lds, int s, int g) {
;     ...
; #pragma unroll 1
;           for (int k0 = ksl; k0 < nkeys; k0 += 256) {
;               f32x4 v[8];
; #pragma unroll
;               for (int u = 0; u < 8; ++u) { const int kk = k0 + 32 * u; const int kc = kk < nkeys ? kk : k0;
;                   if (br == 0) { const u32x2 w = *(const u32x2*)(vcb + (size_t)kc * 64 + 4 * c16); v[u] = (f32x4){bf2f(w.x & 0xffffu), bf2f(w.x >> 16), bf2f(w.y & 0xffffu), bf2f(w.y >> 16)}; }
;                   else v[u] = *(const f32x4*)((const float*)(uintptr_t)VP[kc] + 4 * c16); }
.LBB0_1680:
	v_add_u32_e32 v18, 0xe0, v90
	v_cmp_gt_i32_e64 s[22:23], s2, v18
	s_and_b64 vcc, exec, s[38:39]
	s_mov_b64 s[18:19], -1
	v_cndmask_b32_e64 v68, v90, v18, s[22:23]
	s_cbranch_vccnz .LBB0_1682
	v_lshl_add_u32 v18, v68, 3, 0
	ds_read_b64 v[18:19], v18 offset:16384
	s_mov_b64 s[18:19], 0
	s_waitcnt lgkmcnt(0)
	v_lshl_add_u64 v[18:19], v[18:19], 0, v[70:71]
	global_load_dwordx4 v[18:21], v[18:19], off
